# FFN gate/up phases: workgroups start staggered by (bx>>3)&3 x ~1.3us so epilogue bursts of the four classes do not coincide; 64B-phase padded
# baseline (speedup 1.0000x reference)
; #define LAS __attribute__((address_space(3)))
; __device__ __forceinline__ unsigned xb_add(unsigned* p, unsigned v) { return __hip_atomic_fetch_add(p, v, __ATOMIC_RELAXED, __HIP_MEMORY_SCOPE_AGENT); }
; __device__ __forceinline__ unsigned xb_xcc_id() { return (unsigned)__builtin_amdgcn_s_getreg((3 << 11) | 20) & 0xFu; }
; __device__ __forceinline__ XcdBarrier xcd_barrier_post(unsigned* bar, volatile LAS unsigned* st) {
;     XcdBarrier b; b.bar = bar; b.x = xb_xcc_id(); b.st = st; b.w0 = __builtin_amdgcn_readfirstlane((int)threadIdx.x >> 6);
;     if (threadIdx.x == 0) (void)xb_add(&bar[XB_XCNT(b.x)], 1u);
;     return b;
; __global__ void __launch_bounds__(NTHR, 2) fwd_megakernel(Params p) {
;     ...
;     if (threadIdx.x < 16) ((LAS unsigned*)(lds + LDS_CTL_OFF))[threadIdx.x] = 0u;
;     __syncthreads();
;     const XcdBarrier xbar = xcd_barrier_post((unsigned*)(ws + W_CTL), (volatile LAS unsigned*)(lds + LDS_CTL_OFF));
_Z14fwd_megakernel6Params:
	s_mov_b32 s101, s2
	s_nop 0
	s_nop 0
	s_nop 0
	s_nop 0
	s_nop 0
	s_nop 0
	s_nop 0
	s_nop 0
	s_nop 0
	s_nop 0
	s_nop 0
	s_nop 0
	s_nop 0
	s_nop 0
	s_nop 0
	s_mov_b32 s52, s2
	s_load_dwordx8 s[88:95], s[0:1], 0x100
	s_load_dword s2, s[0:1], 0x128
	v_and_b32_e32 v216, 0x3ff, v0
	v_cmp_gt_u32_e32 vcc, 16, v216
	s_waitcnt lgkmcnt(0)
	v_writelane_b32 v240, s2, 0
	s_load_dwordx2 s[2:3], s[0:1], 0x120
	s_waitcnt lgkmcnt(0)
	v_writelane_b32 v240, s2, 1
	s_nop 1
	v_writelane_b32 v240, s3, 2
	s_add_u32 s2, s0, 0x120
	s_addc_u32 s3, s1, 0
	v_writelane_b32 v240, s2, 3
	s_nop 1
	v_writelane_b32 v240, s3, 4
	s_and_saveexec_b64 s[2:3], vcc
	v_lshl_add_u32 v1, v216, 2, 0
	v_add_u32_e32 v1, 0x23fc0, v1
	v_mov_b32_e32 v2, 0
	ds_write_b32 v1, v2
	s_or_b64 exec, exec, s[2:3]
	s_load_dwordx16 s[36:51], s[0:1], 0x40
	s_add_u32 s2, s94, 0x1f800000
	s_addc_u32 s3, s95, 0
	v_writelane_b32 v240, s2, 5
	s_waitcnt lgkmcnt(0)
	s_barrier
	v_writelane_b32 v240, s3, 6
	s_getreg_b32 s2, hwreg(HW_REG_XCC_ID, 0, 4)
	s_and_b32 s2, s2, 15
	v_writelane_b32 v240, s2, 7
	v_cmp_eq_u32_e64 s[4:5], 0, v216
	s_mov_b64 s[2:3], exec
	s_nop 0
	v_writelane_b32 v240, s4, 8
	s_nop 1
	v_writelane_b32 v240, s5, 9
	s_and_b64 s[4:5], s[2:3], s[4:5]
	s_mov_b64 exec, s[4:5]
	s_cbranch_execz .LBB0_5
	s_mov_b64 s[4:5], exec
	v_mbcnt_lo_u32_b32 v1, s4, 0
	v_mbcnt_hi_u32_b32 v1, s5, v1
	v_cmp_eq_u32_e32 vcc, 0, v1
	s_and_b64 s[6:7], exec, vcc
	s_mov_b64 exec, s[6:7]
	s_cbranch_execz .LBB0_5
	v_readlane_b32 s6, v240, 7
	s_bcnt1_i32_b64 s4, s[4:5]
	s_lshl_b32 s6, s6, 8
	v_mov_b32_e32 v2, s4
	v_readlane_b32 s4, v240, 5
	v_mov_b32_e32 v1, s6
	v_readlane_b32 s5, v240, 6
	s_nop 4
	global_atomic_add v1, v2, s[4:5] offset:1024

;     __host__ __device__ void init(int N, int G_, int c_) { P.init(32768, N, G_, c_); nP = P.nwg; nN = N / BM; nS = 8 * nN; G = G_; c = c_; }
;     __host__ __device__ bool next(int i, Unit& u) const {
;         const long L = (long)i * G + c;
;         if (L < nP) return P.next(i, u);
;         const int j = (int)(L - nP); if (j >= nS) return false;
;         const int hm = j & 7; u.pn = j >> 3; u.pm = 128 + (hm >> 1); u.rb = 32768 + 128 * hm; u.half = 1; u.q = 0; u.cb = u.pn * BM; return true;
; __global__ void __launch_bounds__(NTHR, 2) fwd_megakernel(Params p) {
;     ...
;             pg8::Gemm g{(const pb*)XN, (const pb*)(wl + WL_WUP), MT, DFF, 1024}; pg8::SplitOrder S; S.init(DFF, G, bx);
;             pg8::EpiG E{(pb*)(ws + W_G), p.out + O_FCP + (size_t)l * 4 * 2 * DFF, p.out + O_FCS + (size_t)l * 128 * 2 * DFF, SSb + (size_t)(2 + 3 * l) * MT};
;             for (int rep = 0; rep < REP_G9; ++rep) pg8::gemm_phase<pg8::EpiG, pg8::SplitOrder, true, true>(lds, g, S, E, wave0);
.LBB0_803:
	s_or_b64 exec, exec, s[0:1]
	s_cmpk_gt_i32 s63, 0x57f
	s_cselect_b64 s[2:3], -1, 0
	s_lshl_b32 s0, s63, 7
	s_add_i32 s1, s63, 0xfffffa80
	s_and_b32 s0, s0, 0x380
	s_or_b32 s4, s0, 0x8000
	s_lshr_b32 s0, s1, 3
	v_writelane_b32 v239, s0, 24
	v_mov_b32_e32 v1, v216
	s_waitcnt lgkmcnt(0)
	v_writelane_b32 v239, s1, 25
	v_writelane_b32 v239, s2, 26
	s_barrier
	s_cselect_b32 s99, 1, 0
	s_bfe_u32 s98, s101, 0x20003
	s_cmp_eq_u32 s98, 0
	s_cbranch_scc1 .Lstg_done_0
.Lstg_loop_0:
	s_sleep 44
	s_sub_u32 s98, s98, 1
	s_cmp_lg_u32 s98, 0
	s_cbranch_scc1 .Lstg_loop_0
.Lstg_done_0:
	s_cmp_lg_u32 s99, 0
	s_nop 0
	s_nop 0
	s_nop 0
	s_nop 0
	s_nop 0
	s_nop 0
	s_nop 0
	v_writelane_b32 v239, s3, 27
	v_readfirstlane_b32 s18, v1
	s_and_b64 vcc, exec, s[2:3]
	v_writelane_b32 v239, s1, 28
	s_cbranch_vccz .LBB0_807
	s_mov_b64 s[8:9], 0
	s_cmpk_gt_u32 s1, 0x57
	s_mov_b64 s[2:3], 0
	s_cbranch_scc1 .LBB0_806
	s_mov_b32 s40, 1
	s_mov_b64 s[2:3], -1

;     __host__ __device__ void init(int N, int G_, int c_) { P.init(32768, N, G_, c_); nP = P.nwg; nN = N / BM; nS = 8 * nN; G = G_; c = c_; }
;     __host__ __device__ bool next(int i, Unit& u) const {
;         const long L = (long)i * G + c;
;         if (L < nP) return P.next(i, u);
;         const int j = (int)(L - nP); if (j >= nS) return false;
;         const int hm = j & 7; u.pn = j >> 3; u.pm = 128 + (hm >> 1); u.rb = 32768 + 128 * hm; u.half = 1; u.q = 0; u.cb = u.pn * BM; return true;
; __global__ void __launch_bounds__(NTHR, 2) fwd_megakernel(Params p) {
;     ...
;             pg8::Gemm g{(const pb*)XN, (const pb*)(wl + WL_WUP) + (size_t)DFF * 1024, MT, DFF, 1024}; pg8::SplitOrder S; S.init(DFF, G, bx);
;             pg8::EpiH E{(const pb*)(ws + W_G), (pb*)(ws + W_H), p.in[I_FCW] + (size_t)l * 3 * DFF, p.in[I_FCB] + (size_t)l * DFF, p.in[I_CFC] + (size_t)l * 128 * 2 * DFF, SSb + (size_t)(2 + 3 * l) * MT};
;             for (int rep = 0; rep < REP_G10; ++rep) pg8::gemm_phase<pg8::EpiH, pg8::SplitOrder, true, true>(lds, g, S, E, wave0);
.LBB0_982:
	s_or_b64 exec, exec, s[0:1]
	s_and_b32 s0, s63, 7
	v_writelane_b32 v239, s0, 31
	s_lshl_b32 s0, s0, 7
	v_writelane_b32 v239, s0, 32
	s_bitset1_b32 s0, 15
	v_writelane_b32 v239, s0, 33
	v_mov_b32_e32 v1, v216
	s_waitcnt lgkmcnt(0)
	v_writelane_b32 v239, s1, 34
	s_bfe_u32 s0, s63, 0x20001
	s_bitset1_b32 s0, 7
	v_writelane_b32 v239, s0, 35
	s_barrier
	s_cselect_b32 s99, 1, 0
	s_bfe_u32 s98, s101, 0x20003
	s_cmp_eq_u32 s98, 0
	s_cbranch_scc1 .Lstg_done_1

;     __host__ __device__ bool next(int i, Unit& u) const {
;         const long L = (long)i * G + c;
;         if (L < nP) return P.next(i, u);
;         const int j = (int)(L - nP); if (j >= nS) return false;
;         const int hm = j & 7; u.pn = j >> 3; u.pm = 128 + (hm >> 1); u.rb = 32768 + 128 * hm; u.half = 1; u.q = 0; u.cb = u.pn * BM; return true;
.Lstg_done_1:
	s_cmp_lg_u32 s99, 0
	s_nop 0
	s_nop 0
	s_nop 0
	s_nop 0
	s_nop 0
	s_nop 0
	v_readlane_b32 s0, v239, 26
	v_readlane_b32 s1, v239, 27
	s_and_b64 vcc, exec, s[0:1]
	v_readfirstlane_b32 s4, v1
	s_cbranch_vccz .LBB0_986
	v_readlane_b32 s0, v239, 28
	s_mov_b64 s[8:9], 0
	s_cmpk_gt_u32 s0, 0x57
	s_mov_b64 s[0:1], 0
	s_cbranch_scc1 .LBB0_985
	s_mov_b32 s60, 1
	s_mov_b64 s[0:1], -1

;     __host__ __device__ void init(int N, int G_, int c_) { P.init(32768, N, G_, c_); nP = P.nwg; nN = N / BM; nS = 8 * nN; G = G_; c = c_; }
;     __host__ __device__ bool next(int i, Unit& u) const {
;         const long L = (long)i * G + c;
;         if (L < nP) return P.next(i, u);
; __global__ void __launch_bounds__(NTHR, 2) fwd_megakernel(Params p) {
;     ...
;             pg8::Gemm g{(const pb*)XN, (const pb*)(wl + WL_WUP), MT, DFF, 1024}; pg8::SplitOrder S; S.init(DFF, G, bx);
;             pg8::EpiG E{(pb*)(ws + W_G), p.out + O_FCP + (size_t)l * 4 * 2 * DFF, p.out + O_FCS + (size_t)l * 128 * 2 * DFF, SSb + (size_t)(2 + 3 * l) * MT};
;             for (int rep = 0; rep < REP_G9; ++rep) pg8::gemm_phase<pg8::EpiG, pg8::SplitOrder, true, true>(lds, g, S, E, wave0);
.LBB0_2934:
	s_or_b64 exec, exec, s[0:1]
	v_readlane_b32 s0, v239, 26
	v_mov_b32_e32 v1, v216
	v_readlane_b32 s1, v239, 27
	s_waitcnt lgkmcnt(0)
	s_barrier
	s_cselect_b32 s99, 1, 0
	s_bfe_u32 s98, s101, 0x20003
	s_cmp_eq_u32 s98, 0
	s_cbranch_scc1 .Lstg_done_2

;     __host__ __device__ bool next(int i, Unit& u) const {
;         const long L = (long)i * G + c;
;         if (L < nP) return P.next(i, u);
;         const int j = (int)(L - nP); if (j >= nS) return false;
;         const int hm = j & 7; u.pn = j >> 3; u.pm = 128 + (hm >> 1); u.rb = 32768 + 128 * hm; u.half = 1; u.q = 0; u.cb = u.pn * BM; return true;
.Lstg_done_2:
	s_cmp_lg_u32 s99, 0
	s_nop 0
	s_nop 0
	s_nop 0
	s_nop 0
	s_nop 0
	s_nop 0
	s_and_b64 vcc, exec, s[0:1]
	v_readfirstlane_b32 s14, v1
	s_cbranch_vccz .LBB0_2938
	s_mov_b64 s[4:5], 0
	s_cmpk_gt_u32 s61, 0x57
	s_mov_b64 s[2:3], 0
	s_cbranch_scc1 .LBB0_2937
	s_mov_b32 s26, 1
	s_mov_b64 s[2:3], -1

;     __host__ __device__ void init(int N, int G_, int c_) { P.init(32768, N, G_, c_); nP = P.nwg; nN = N / BM; nS = 8 * nN; G = G_; c = c_; }
;     __host__ __device__ bool next(int i, Unit& u) const {
;         const long L = (long)i * G + c;
;         if (L < nP) return P.next(i, u);
;         const int j = (int)(L - nP); if (j >= nS) return false;
;         const int hm = j & 7; u.pn = j >> 3; u.pm = 128 + (hm >> 1); u.rb = 32768 + 128 * hm; u.half = 1; u.q = 0; u.cb = u.pn * BM; return true;
; __global__ void __launch_bounds__(NTHR, 2) fwd_megakernel(Params p) {
;     ...
;             pg8::Gemm g{(const pb*)XN, (const pb*)(wl + WL_WUP) + (size_t)DFF * 1024, MT, DFF, 1024}; pg8::SplitOrder S; S.init(DFF, G, bx);
;             pg8::EpiH E{(const pb*)(ws + W_G), (pb*)(ws + W_H), p.in[I_FCW] + (size_t)l * 3 * DFF, p.in[I_FCB] + (size_t)l * DFF, p.in[I_CFC] + (size_t)l * 128 * 2 * DFF, SSb + (size_t)(2 + 3 * l) * MT};
;             for (int rep = 0; rep < REP_G10; ++rep) pg8::gemm_phase<pg8::EpiH, pg8::SplitOrder, true, true>(lds, g, S, E, wave0);
.Lstg_done_3:
	s_cmp_lg_u32 s99, 0
	s_nop 0
	s_nop 0
	s_nop 0
	s_nop 0
	s_nop 0
	s_nop 0
	s_and_b64 vcc, exec, s[0:1]
	v_readfirstlane_b32 s8, v1
	s_cbranch_vccz .LBB0_3116
	s_mov_b64 s[2:3], 0
	s_cmpk_gt_u32 s61, 0x57
	s_mov_b64 s[0:1], 0
	s_cbranch_scc1 .LBB0_3117
	s_mov_b32 s56, 1
	s_mov_b64 s[0:1], -1
	s_branch .LBB0_3117
